# attention item epilogues: gate loads issued together (phase 7 had a load/wait/store ladder), rows stored as 4x dwordx4 after permlane32_swap instead of 8x dwordx2
# speedup vs baseline: 1.0075x; 1.0075x over previous
.LBB0_51:
	v_mov_b32_e32 v75, v74
	v_pk_fma_f32 v[50:51], v[50:51], s[54:55], v[74:75] op_sel_hi:[1,0,1]
	v_pk_fma_f32 v[52:53], v[52:53], s[54:55], v[74:75] op_sel_hi:[1,0,1]
	v_exp_f32_e32 v50, v50
	v_exp_f32_e32 v51, v51
	v_exp_f32_e32 v52, v52
	v_exp_f32_e32 v53, v53
	v_pk_fma_f32 v[54:55], v[54:55], s[54:55], v[74:75] op_sel_hi:[1,0,1]
	v_pk_fma_f32 v[56:57], v[56:57], s[54:55], v[74:75] op_sel_hi:[1,0,1]
	v_exp_f32_e32 v54, v54
	v_exp_f32_e32 v55, v55
	v_exp_f32_e32 v56, v56
	v_exp_f32_e32 v57, v57
	v_pk_fma_f32 v[58:59], v[58:59], s[54:55], v[74:75] op_sel_hi:[1,0,1]
	v_pk_add_f32 v[78:79], v[50:51], 0 op_sel_hi:[1,0]
	v_exp_f32_e32 v58, v58
	v_exp_f32_e32 v59, v59
	v_pk_fma_f32 v[60:61], v[60:61], s[54:55], v[74:75] op_sel_hi:[1,0,1]
	v_pk_add_f32 v[78:79], v[52:53], v[78:79]
	v_exp_f32_e32 v60, v60
	v_exp_f32_e32 v61, v61
	v_pk_fma_f32 v[62:63], v[62:63], s[54:55], v[74:75] op_sel_hi:[1,0,1]
	v_pk_add_f32 v[78:79], v[54:55], v[78:79]
	v_exp_f32_e32 v62, v62
	v_exp_f32_e32 v63, v63
	v_pk_fma_f32 v[64:65], v[64:65], s[54:55], v[74:75] op_sel_hi:[1,0,1]
	v_pk_add_f32 v[78:79], v[56:57], v[78:79]
	v_exp_f32_e32 v64, v64
	v_exp_f32_e32 v65, v65
	v_pk_fma_f32 v[34:35], v[34:35], s[54:55], v[74:75] op_sel_hi:[1,0,1]
	v_pk_add_f32 v[78:79], v[58:59], v[78:79]
	v_exp_f32_e32 v80, v34
	v_exp_f32_e32 v81, v35
	v_pk_fma_f32 v[34:35], v[36:37], s[54:55], v[74:75] op_sel_hi:[1,0,1]
	v_pk_add_f32 v[78:79], v[60:61], v[78:79]
	v_exp_f32_e32 v82, v34
	v_exp_f32_e32 v83, v35
	v_pk_fma_f32 v[34:35], v[38:39], s[54:55], v[74:75] op_sel_hi:[1,0,1]
	v_pk_add_f32 v[78:79], v[62:63], v[78:79]
	v_exp_f32_e32 v84, v34
	v_exp_f32_e32 v85, v35
	v_pk_fma_f32 v[34:35], v[40:41], s[54:55], v[74:75] op_sel_hi:[1,0,1]
	v_pk_add_f32 v[78:79], v[64:65], v[78:79]
	v_exp_f32_e32 v86, v34
	v_exp_f32_e32 v87, v35
	v_pk_fma_f32 v[36:37], v[42:43], s[54:55], v[74:75] op_sel_hi:[1,0,1]
	v_pk_add_f32 v[34:35], v[80:81], v[78:79]
	v_exp_f32_e32 v78, v36
	v_exp_f32_e32 v79, v37
	v_pk_fma_f32 v[36:37], v[44:45], s[54:55], v[74:75] op_sel_hi:[1,0,1]
	v_pk_add_f32 v[34:35], v[82:83], v[34:35]
	v_exp_f32_e32 v88, v36
	v_exp_f32_e32 v89, v37
	v_pk_fma_f32 v[36:37], v[46:47], s[54:55], v[74:75] op_sel_hi:[1,0,1]
	v_pk_add_f32 v[34:35], v[84:85], v[34:35]
	v_exp_f32_e32 v90, v36
	v_exp_f32_e32 v91, v37
	v_pk_fma_f32 v[36:37], v[48:49], s[54:55], v[74:75] op_sel_hi:[1,0,1]
	v_pk_add_f32 v[34:35], v[86:87], v[34:35]
	v_exp_f32_e32 v74, v36
	v_exp_f32_e32 v75, v37
	s_lshl_b32 s8, s34, 1
	v_pk_add_f32 v[34:35], v[78:79], v[34:35]
	s_add_u32 s10, s25, s8
	v_pk_add_f32 v[34:35], v[88:89], v[34:35]
	s_addc_u32 s11, s26, 0
	v_pk_add_f32 v[34:35], v[90:91], v[34:35]
	s_add_u32 s8, s27, s8
	v_pk_add_f32 v[34:35], v[74:75], v[34:35]
	s_addc_u32 s9, s28, 0
	v_add_f32_e32 v92, v34, v35
	s_setprio 1
	ds_read2_b64 v[38:41], v77 offset0:132 offset1:134
	ds_read2_b64 v[42:45], v76 offset0:164 offset1:166
	v_cvt_pk_bf16_f32 v34, v50, v51
	v_cvt_pk_bf16_f32 v35, v52, v53
	v_cvt_pk_bf16_f32 v36, v54, v55
	v_cvt_pk_bf16_f32 v37, v56, v57
	s_waitcnt lgkmcnt(3)
	s_nop 0
	v_mfma_f32_32x32x16_bf16 v[18:33], v[66:69], v[34:37], v[18:33]
	s_waitcnt lgkmcnt(2)
	v_mfma_f32_32x32x16_bf16 v[2:17], v[70:73], v[34:37], v[2:17]
	ds_read2_b64 v[46:49], v77 offset0:136 offset1:138
	ds_read2_b64 v[50:53], v76 offset0:168 offset1:170
	v_cvt_pk_bf16_f32 v34, v58, v59
	v_cvt_pk_bf16_f32 v35, v60, v61
	v_cvt_pk_bf16_f32 v36, v62, v63
	v_cvt_pk_bf16_f32 v37, v64, v65
	s_waitcnt lgkmcnt(3)
	s_nop 0
	v_mfma_f32_32x32x16_bf16 v[18:33], v[38:41], v[34:37], v[18:33]
	s_waitcnt lgkmcnt(2)
	v_mfma_f32_32x32x16_bf16 v[2:17], v[42:45], v[34:37], v[2:17]
	ds_read2_b64 v[38:41], v77 offset0:140 offset1:142
	ds_read2_b64 v[42:45], v76 offset0:172 offset1:174
	v_cvt_pk_bf16_f32 v34, v80, v81
	v_cvt_pk_bf16_f32 v35, v82, v83
	v_cvt_pk_bf16_f32 v36, v84, v85
	v_cvt_pk_bf16_f32 v37, v86, v87
	s_waitcnt lgkmcnt(3)
	s_nop 0
	v_mfma_f32_32x32x16_bf16 v[18:33], v[46:49], v[34:37], v[18:33]
	s_waitcnt lgkmcnt(2)
	v_mfma_f32_32x32x16_bf16 v[2:17], v[50:53], v[34:37], v[2:17]
	v_cvt_pk_bf16_f32 v34, v78, v79
	v_cvt_pk_bf16_f32 v35, v88, v89
	v_cvt_pk_bf16_f32 v36, v90, v91
	v_cvt_pk_bf16_f32 v37, v74, v75
	s_waitcnt lgkmcnt(1)
	s_nop 0
	v_mfma_f32_32x32x16_bf16 v[18:33], v[38:41], v[34:37], v[18:33]
	s_waitcnt lgkmcnt(0)
	v_mfma_f32_32x32x16_bf16 v[2:17], v[42:45], v[34:37], v[2:17]
	v_add_f32_e32 v50, v127, v92
	s_setprio 0
	v_lshlrev_b64 v[34:35], 10, v[170:171]
	v_lshl_add_u64 v[34:35], s[10:11], 0, v[34:35]
	v_lshl_add_u64 v[34:35], v[34:35], 0, v[0:1]
	s_barrier
	global_load_dwordx2 v[36:37], v[34:35], off
	global_load_dwordx2 v[38:39], v[34:35], off offset:16
	global_load_dwordx2 v[40:41], v[34:35], off offset:32
	global_load_dwordx2 v[42:43], v[34:35], off offset:48
	global_load_dwordx2 v[44:45], v[34:35], off offset:64
	global_load_dwordx2 v[46:47], v[34:35], off offset:80
	v_mov_b32_e32 v51, v50
	s_nop 1
	v_permlane32_swap_b32_e32 v50, v51
	v_add_f32_e32 v52, v50, v51
	global_load_dwordx2 v[50:51], v[34:35], off offset:96
	v_lshlrev_b64 v[48:49], 11, v[170:171]
	global_load_dwordx2 v[34:35], v[34:35], off offset:112
	v_lshl_add_u64 v[48:49], s[8:9], 0, v[48:49]
	v_div_scale_f32 v53, s[8:9], v52, v52, 1.0
	v_rcp_f32_e32 v54, v53
	v_div_scale_f32 v55, vcc, 1.0, v52, 1.0
	v_lshl_add_u64 v[48:49], v[48:49], 0, v[0:1]
	v_fma_f32 v56, -v53, v54, 1.0
	v_fmac_f32_e32 v54, v56, v54
	v_mul_f32_e32 v56, v55, v54
	v_fma_f32 v57, -v53, v56, v55
	v_fmac_f32_e32 v56, v57, v54
	v_fma_f32 v53, -v53, v56, v55
	v_div_fmas_f32 v53, v53, v54, v56
	v_div_fixup_f32 v52, v53, v52, 1.0
	s_add_i32 s31, s31, s29
	s_add_i32 s30, s30, s29
	s_cmpk_gt_i32 s31, 0x5ff
	s_waitcnt vmcnt(7)
	v_lshlrev_b32_e32 v54, 16, v36
	v_and_b32_e32 v55, 0xffff0000, v36
	v_lshlrev_b32_e32 v56, 16, v37
	v_and_b32_e32 v57, 0xffff0000, v37
	v_mul_f32_e32 v58, v18, v52
	v_mul_f32_e32 v59, v19, v52
	v_mul_f32_e32 v60, v20, v52
	v_mul_f32_e32 v61, v21, v52
	v_mul_f32_e32 v58, v58, v54
	v_mul_f32_e32 v59, v59, v55
	v_mul_f32_e32 v60, v60, v56
	v_mul_f32_e32 v61, v61, v57
	v_cvt_pk_bf16_f32 v18, v58, v59
	v_cvt_pk_bf16_f32 v19, v60, v61
	s_waitcnt vmcnt(6)
	v_lshlrev_b32_e32 v54, 16, v38
	v_and_b32_e32 v55, 0xffff0000, v38
	v_lshlrev_b32_e32 v56, 16, v39
	v_and_b32_e32 v57, 0xffff0000, v39
	v_mul_f32_e32 v58, v22, v52
	v_mul_f32_e32 v59, v23, v52
	v_mul_f32_e32 v60, v24, v52
	v_mul_f32_e32 v61, v25, v52
	v_mul_f32_e32 v58, v58, v54
	v_mul_f32_e32 v59, v59, v55
	v_mul_f32_e32 v60, v60, v56
	v_mul_f32_e32 v61, v61, v57
	v_cvt_pk_bf16_f32 v20, v58, v59
	v_cvt_pk_bf16_f32 v21, v60, v61
	s_waitcnt vmcnt(5)
	v_lshlrev_b32_e32 v54, 16, v40
	v_and_b32_e32 v55, 0xffff0000, v40
	v_lshlrev_b32_e32 v56, 16, v41
	v_and_b32_e32 v57, 0xffff0000, v41
	v_mul_f32_e32 v58, v26, v52
	v_mul_f32_e32 v59, v27, v52
	v_mul_f32_e32 v60, v28, v52
	v_mul_f32_e32 v61, v29, v52
	v_mul_f32_e32 v58, v58, v54
	v_mul_f32_e32 v59, v59, v55
	v_mul_f32_e32 v60, v60, v56
	v_mul_f32_e32 v61, v61, v57
	v_cvt_pk_bf16_f32 v22, v58, v59
	v_cvt_pk_bf16_f32 v23, v60, v61
	s_waitcnt vmcnt(4)
	v_lshlrev_b32_e32 v54, 16, v42
	v_and_b32_e32 v55, 0xffff0000, v42
	v_lshlrev_b32_e32 v56, 16, v43
	v_and_b32_e32 v57, 0xffff0000, v43
	v_mul_f32_e32 v58, v30, v52
	v_mul_f32_e32 v59, v31, v52
	v_mul_f32_e32 v60, v32, v52
	v_mul_f32_e32 v61, v33, v52
	v_mul_f32_e32 v58, v58, v54
	v_mul_f32_e32 v59, v59, v55
	v_mul_f32_e32 v60, v60, v56
	v_mul_f32_e32 v61, v61, v57
	v_cvt_pk_bf16_f32 v24, v58, v59
	v_cvt_pk_bf16_f32 v25, v60, v61
	s_waitcnt vmcnt(3)
	v_lshlrev_b32_e32 v54, 16, v44
	v_and_b32_e32 v55, 0xffff0000, v44
	v_lshlrev_b32_e32 v56, 16, v45
	v_and_b32_e32 v57, 0xffff0000, v45
	v_mul_f32_e32 v58, v2, v52
	v_mul_f32_e32 v59, v3, v52
	v_mul_f32_e32 v60, v4, v52
	v_mul_f32_e32 v61, v5, v52
	v_mul_f32_e32 v58, v58, v54
	v_mul_f32_e32 v59, v59, v55
	v_mul_f32_e32 v60, v60, v56
	v_mul_f32_e32 v61, v61, v57
	v_cvt_pk_bf16_f32 v26, v58, v59
	v_cvt_pk_bf16_f32 v27, v60, v61
	s_waitcnt vmcnt(2)
	v_lshlrev_b32_e32 v54, 16, v46
	v_and_b32_e32 v55, 0xffff0000, v46
	v_lshlrev_b32_e32 v56, 16, v47
	v_and_b32_e32 v57, 0xffff0000, v47
	v_mul_f32_e32 v58, v6, v52
	v_mul_f32_e32 v59, v7, v52
	v_mul_f32_e32 v60, v8, v52
	v_mul_f32_e32 v61, v9, v52
	v_mul_f32_e32 v58, v58, v54
	v_mul_f32_e32 v59, v59, v55
	v_mul_f32_e32 v60, v60, v56
	v_mul_f32_e32 v61, v61, v57
	v_cvt_pk_bf16_f32 v28, v58, v59
	v_cvt_pk_bf16_f32 v29, v60, v61
	s_waitcnt vmcnt(1)
	v_lshlrev_b32_e32 v54, 16, v50
	v_and_b32_e32 v55, 0xffff0000, v50
	v_lshlrev_b32_e32 v56, 16, v51
	v_and_b32_e32 v57, 0xffff0000, v51
	v_mul_f32_e32 v58, v10, v52
	v_mul_f32_e32 v59, v11, v52
	v_mul_f32_e32 v60, v12, v52
	v_mul_f32_e32 v61, v13, v52
	v_mul_f32_e32 v58, v58, v54
	v_mul_f32_e32 v59, v59, v55
	v_mul_f32_e32 v60, v60, v56
	v_mul_f32_e32 v61, v61, v57
	v_cvt_pk_bf16_f32 v30, v58, v59
	v_cvt_pk_bf16_f32 v31, v60, v61
	s_waitcnt vmcnt(0)
	v_lshlrev_b32_e32 v54, 16, v34
	v_and_b32_e32 v55, 0xffff0000, v34
	v_lshlrev_b32_e32 v56, 16, v35
	v_and_b32_e32 v57, 0xffff0000, v35
	v_mul_f32_e32 v58, v14, v52
	v_mul_f32_e32 v59, v15, v52
	v_mul_f32_e32 v60, v16, v52
	v_mul_f32_e32 v61, v17, v52
	v_mul_f32_e32 v58, v58, v54
	v_mul_f32_e32 v59, v59, v55
	v_mul_f32_e32 v60, v60, v56
	v_mul_f32_e32 v61, v61, v57
	v_cvt_pk_bf16_f32 v32, v58, v59
	v_cvt_pk_bf16_f32 v33, v60, v61
	v_mbcnt_lo_u32_b32 v62, -1, 0
	v_mbcnt_hi_u32_b32 v62, -1, v62
	v_and_b32_e32 v62, 32, v62
	v_lshrrev_b32_e32 v62, 2, v62
	v_mov_b32_e32 v63, 0
	v_lshl_add_u64 v[48:49], v[48:49], 0, v[62:63]
	v_permlane32_swap_b32_e32 v18, v20
	v_permlane32_swap_b32_e32 v19, v21
	v_permlane32_swap_b32_e32 v22, v24
	v_permlane32_swap_b32_e32 v23, v25
	v_permlane32_swap_b32_e32 v26, v28
	v_permlane32_swap_b32_e32 v27, v29
	v_permlane32_swap_b32_e32 v30, v32
	v_permlane32_swap_b32_e32 v31, v33
	global_store_dwordx4 v[48:49], v[18:21], off
	global_store_dwordx4 v[48:49], v[22:25], off offset:32
	global_store_dwordx4 v[48:49], v[26:29], off offset:64
	global_store_dwordx4 v[48:49], v[30:33], off offset:96
	s_cbranch_scc1 .LBB0_69

.LBB0_184:
	s_add_u32 s2, s86, s73
	s_addc_u32 s3, s87, 0
	v_lshl_add_u64 v[2:3], s[2:3], 0, v[162:163]
	v_add_f32_e32 v0, v151, v4
	v_mov_b32_e32 v145, v1
	v_lshl_add_u64 v[6:7], v[2:3], 0, v[144:145]
	global_load_dwordx2 v[240:241], v[6:7], off
	global_load_dwordx2 v[242:243], v[6:7], off offset:16
	global_load_dwordx2 v[244:245], v[6:7], off offset:32
	global_load_dwordx2 v[246:247], v[6:7], off offset:48
	global_load_dwordx2 v[248:249], v[6:7], off offset:64
	global_load_dwordx2 v[250:251], v[6:7], off offset:80
	global_load_dwordx2 v[222:223], v[6:7], off offset:96
	global_load_dwordx2 v[218:219], v[6:7], off offset:112
	v_div_scale_f32 v14, s[2:3], v0, v0, 1.0
	v_rcp_f32_e32 v48, v14
	v_div_scale_f32 v15, vcc, 1.0, v0, 1.0
	s_add_u32 s2, s88, s73
	v_fma_f32 v49, -v14, v48, 1.0
	v_fmac_f32_e32 v48, v49, v48
	v_mul_f32_e32 v49, v15, v48
	v_fma_f32 v50, -v14, v49, v15
	v_fmac_f32_e32 v49, v50, v48
	v_fma_f32 v14, -v14, v49, v15
	v_div_fmas_f32 v14, v14, v48, v49
	v_div_fixup_f32 v0, v14, v0, 1.0
	v_lshlrev_b64 v[4:5], 11, v[160:161]
	s_addc_u32 s3, s89, 0
	v_lshl_add_u64 v[4:5], s[2:3], 0, v[4:5]
	v_lshl_add_u64 v[12:13], v[4:5], 0, v[144:145]
	v_mov_b32_e32 v149, v1
	v_mov_b32_e32 v151, v1
	v_mov_b32_e32 v153, v1
	v_mov_b32_e32 v155, v1
	v_mov_b32_e32 v157, v1
	v_mov_b32_e32 v159, v1
	s_add_i32 s72, s72, s90
	s_add_i32 s50, s50, s90
	s_cmpk_gt_i32 s72, 0x5ff
	s_movk_i32 s43, 0x1fff
	s_mov_b32 s42, 0x800000
	s_waitcnt vmcnt(7)
	v_lshlrev_b32_e32 v8, 16, v240
	v_and_b32_e32 v9, 0xffff0000, v240
	v_lshlrev_b32_e32 v10, 16, v241
	v_and_b32_e32 v11, 0xffff0000, v241
	v_mul_f32_e32 v14, v32, v0
	v_mul_f32_e32 v15, v33, v0
	v_mul_f32_e32 v48, v34, v0
	v_mul_f32_e32 v49, v35, v0
	v_mul_f32_e32 v14, v14, v8
	v_mul_f32_e32 v15, v15, v9
	v_mul_f32_e32 v48, v48, v10
	v_mul_f32_e32 v49, v49, v11
	v_cvt_pk_bf16_f32 v32, v14, v15
	v_cvt_pk_bf16_f32 v33, v48, v49
	s_waitcnt vmcnt(6)
	v_lshlrev_b32_e32 v8, 16, v242
	v_and_b32_e32 v9, 0xffff0000, v242
	v_lshlrev_b32_e32 v10, 16, v243
	v_and_b32_e32 v11, 0xffff0000, v243
	v_mul_f32_e32 v14, v36, v0
	v_mul_f32_e32 v15, v37, v0
	v_mul_f32_e32 v48, v38, v0
	v_mul_f32_e32 v49, v39, v0
	v_mul_f32_e32 v14, v14, v8
	v_mul_f32_e32 v15, v15, v9
	v_mul_f32_e32 v48, v48, v10
	v_mul_f32_e32 v49, v49, v11
	v_cvt_pk_bf16_f32 v34, v14, v15
	v_cvt_pk_bf16_f32 v35, v48, v49
	s_waitcnt vmcnt(5)
	v_lshlrev_b32_e32 v8, 16, v244
	v_and_b32_e32 v9, 0xffff0000, v244
	v_lshlrev_b32_e32 v10, 16, v245
	v_and_b32_e32 v11, 0xffff0000, v245
	v_mul_f32_e32 v14, v40, v0
	v_mul_f32_e32 v15, v41, v0
	v_mul_f32_e32 v48, v42, v0
	v_mul_f32_e32 v49, v43, v0
	v_mul_f32_e32 v14, v14, v8
	v_mul_f32_e32 v15, v15, v9
	v_mul_f32_e32 v48, v48, v10
	v_mul_f32_e32 v49, v49, v11
	v_cvt_pk_bf16_f32 v36, v14, v15
	v_cvt_pk_bf16_f32 v37, v48, v49
	s_waitcnt vmcnt(4)
	v_lshlrev_b32_e32 v8, 16, v246
	v_and_b32_e32 v9, 0xffff0000, v246
	v_lshlrev_b32_e32 v10, 16, v247
	v_and_b32_e32 v11, 0xffff0000, v247
	v_mul_f32_e32 v14, v44, v0
	v_mul_f32_e32 v15, v45, v0
	v_mul_f32_e32 v48, v46, v0
	v_mul_f32_e32 v49, v47, v0
	v_mul_f32_e32 v14, v14, v8
	v_mul_f32_e32 v15, v15, v9
	v_mul_f32_e32 v48, v48, v10
	v_mul_f32_e32 v49, v49, v11
	v_cvt_pk_bf16_f32 v38, v14, v15
	v_cvt_pk_bf16_f32 v39, v48, v49
	s_waitcnt vmcnt(3)
	v_lshlrev_b32_e32 v8, 16, v248
	v_and_b32_e32 v9, 0xffff0000, v248
	v_lshlrev_b32_e32 v10, 16, v249
	v_and_b32_e32 v11, 0xffff0000, v249
	v_mul_f32_e32 v14, v16, v0
	v_mul_f32_e32 v15, v17, v0
	v_mul_f32_e32 v48, v18, v0
	v_mul_f32_e32 v49, v19, v0
	v_mul_f32_e32 v14, v14, v8
	v_mul_f32_e32 v15, v15, v9
	v_mul_f32_e32 v48, v48, v10
	v_mul_f32_e32 v49, v49, v11
	v_cvt_pk_bf16_f32 v40, v14, v15
	v_cvt_pk_bf16_f32 v41, v48, v49
	s_waitcnt vmcnt(2)
	v_lshlrev_b32_e32 v8, 16, v250
	v_and_b32_e32 v9, 0xffff0000, v250
	v_lshlrev_b32_e32 v10, 16, v251
	v_and_b32_e32 v11, 0xffff0000, v251
	v_mul_f32_e32 v14, v20, v0
	v_mul_f32_e32 v15, v21, v0
	v_mul_f32_e32 v48, v22, v0
	v_mul_f32_e32 v49, v23, v0
	v_mul_f32_e32 v14, v14, v8
	v_mul_f32_e32 v15, v15, v9
	v_mul_f32_e32 v48, v48, v10
	v_mul_f32_e32 v49, v49, v11
	v_cvt_pk_bf16_f32 v42, v14, v15
	v_cvt_pk_bf16_f32 v43, v48, v49
	s_waitcnt vmcnt(1)
	v_lshlrev_b32_e32 v8, 16, v222
	v_and_b32_e32 v9, 0xffff0000, v222
	v_lshlrev_b32_e32 v10, 16, v223
	v_and_b32_e32 v11, 0xffff0000, v223
	v_mul_f32_e32 v14, v24, v0
	v_mul_f32_e32 v15, v25, v0
	v_mul_f32_e32 v48, v26, v0
	v_mul_f32_e32 v49, v27, v0
	v_mul_f32_e32 v14, v14, v8
	v_mul_f32_e32 v15, v15, v9
	v_mul_f32_e32 v48, v48, v10
	v_mul_f32_e32 v49, v49, v11
	v_cvt_pk_bf16_f32 v44, v14, v15
	v_cvt_pk_bf16_f32 v45, v48, v49
	s_waitcnt vmcnt(0)
	v_lshlrev_b32_e32 v8, 16, v218
	v_and_b32_e32 v9, 0xffff0000, v218
	v_lshlrev_b32_e32 v10, 16, v219
	v_and_b32_e32 v11, 0xffff0000, v219
	v_mul_f32_e32 v14, v28, v0
	v_mul_f32_e32 v15, v29, v0
	v_mul_f32_e32 v48, v30, v0
	v_mul_f32_e32 v49, v31, v0
	v_mul_f32_e32 v14, v14, v8
	v_mul_f32_e32 v15, v15, v9
	v_mul_f32_e32 v48, v48, v10
	v_mul_f32_e32 v49, v49, v11
	v_cvt_pk_bf16_f32 v46, v14, v15
	v_cvt_pk_bf16_f32 v47, v48, v49
	v_mbcnt_lo_u32_b32 v2, -1, 0
	v_mbcnt_hi_u32_b32 v2, -1, v2
	v_and_b32_e32 v2, 32, v2
	v_lshrrev_b32_e32 v2, 2, v2
	v_mov_b32_e32 v3, 0
	v_lshl_add_u64 v[12:13], v[12:13], 0, v[2:3]
	v_permlane32_swap_b32_e32 v32, v34
	v_permlane32_swap_b32_e32 v33, v35
	v_permlane32_swap_b32_e32 v36, v38
	v_permlane32_swap_b32_e32 v37, v39
	v_permlane32_swap_b32_e32 v40, v42
	v_permlane32_swap_b32_e32 v41, v43
	v_permlane32_swap_b32_e32 v44, v46
	v_permlane32_swap_b32_e32 v45, v47
	global_store_dwordx4 v[12:13], v[32:35], off
	global_store_dwordx4 v[12:13], v[36:39], off offset:32
	global_store_dwordx4 v[12:13], v[40:43], off offset:64
	global_store_dwordx4 v[12:13], v[44:47], off offset:96
	s_cbranch_scc1 .LBB0_298

.LBB0_790:
	v_mov_b32_e32 v11, v10
	v_pk_fma_f32 v[14:15], v[64:65], s[58:59], v[10:11] op_sel_hi:[1,0,1]
	v_pk_fma_f32 v[64:65], v[66:67], s[58:59], v[10:11] op_sel_hi:[1,0,1]
	v_exp_f32_e32 v14, v14
	v_exp_f32_e32 v15, v15
	v_exp_f32_e32 v64, v64
	v_exp_f32_e32 v65, v65
	v_pk_fma_f32 v[66:67], v[68:69], s[58:59], v[10:11] op_sel_hi:[1,0,1]
	v_pk_fma_f32 v[68:69], v[70:71], s[58:59], v[10:11] op_sel_hi:[1,0,1]
	v_exp_f32_e32 v66, v66
	v_exp_f32_e32 v67, v67
	v_exp_f32_e32 v68, v68
	v_exp_f32_e32 v69, v69
	v_pk_fma_f32 v[72:73], v[72:73], s[58:59], v[10:11] op_sel_hi:[1,0,1]
	v_pk_add_f32 v[70:71], v[14:15], 0 op_sel_hi:[1,0]
	v_exp_f32_e32 v72, v72
	v_exp_f32_e32 v73, v73
	v_pk_fma_f32 v[74:75], v[74:75], s[58:59], v[10:11] op_sel_hi:[1,0,1]
	v_pk_add_f32 v[70:71], v[64:65], v[70:71]
	v_exp_f32_e32 v74, v74
	v_exp_f32_e32 v75, v75
	v_pk_fma_f32 v[76:77], v[76:77], s[58:59], v[10:11] op_sel_hi:[1,0,1]
	v_pk_add_f32 v[70:71], v[66:67], v[70:71]
	v_exp_f32_e32 v76, v76
	v_exp_f32_e32 v77, v77
	v_pk_fma_f32 v[78:79], v[78:79], s[58:59], v[10:11] op_sel_hi:[1,0,1]
	v_pk_add_f32 v[70:71], v[68:69], v[70:71]
	v_exp_f32_e32 v78, v78
	v_exp_f32_e32 v79, v79
	v_pk_fma_f32 v[48:49], v[48:49], s[58:59], v[10:11] op_sel_hi:[1,0,1]
	v_pk_add_f32 v[70:71], v[72:73], v[70:71]
	v_exp_f32_e32 v80, v48
	v_exp_f32_e32 v81, v49
	v_pk_fma_f32 v[48:49], v[50:51], s[58:59], v[10:11] op_sel_hi:[1,0,1]
	v_pk_add_f32 v[70:71], v[74:75], v[70:71]
	v_exp_f32_e32 v82, v48
	v_exp_f32_e32 v83, v49
	v_pk_fma_f32 v[48:49], v[52:53], s[58:59], v[10:11] op_sel_hi:[1,0,1]
	v_pk_add_f32 v[70:71], v[76:77], v[70:71]
	v_exp_f32_e32 v84, v48
	v_exp_f32_e32 v85, v49
	v_pk_fma_f32 v[48:49], v[54:55], s[58:59], v[10:11] op_sel_hi:[1,0,1]
	v_pk_add_f32 v[70:71], v[78:79], v[70:71]
	v_exp_f32_e32 v86, v48
	v_exp_f32_e32 v87, v49
	v_pk_fma_f32 v[50:51], v[56:57], s[58:59], v[10:11] op_sel_hi:[1,0,1]
	v_pk_add_f32 v[48:49], v[80:81], v[70:71]
	v_exp_f32_e32 v70, v50
	v_exp_f32_e32 v71, v51
	v_pk_fma_f32 v[50:51], v[58:59], s[58:59], v[10:11] op_sel_hi:[1,0,1]
	v_pk_add_f32 v[48:49], v[82:83], v[48:49]
	v_exp_f32_e32 v88, v50
	v_exp_f32_e32 v89, v51
	v_pk_fma_f32 v[50:51], v[60:61], s[58:59], v[10:11] op_sel_hi:[1,0,1]
	v_pk_add_f32 v[48:49], v[84:85], v[48:49]
	v_exp_f32_e32 v60, v50
	v_exp_f32_e32 v61, v51
	v_pk_fma_f32 v[10:11], v[62:63], s[58:59], v[10:11] op_sel_hi:[1,0,1]
	v_pk_add_f32 v[48:49], v[86:87], v[48:49]
	v_exp_f32_e32 v62, v10
	v_exp_f32_e32 v63, v11
	v_pk_add_f32 v[10:11], v[70:71], v[48:49]
	s_lshl_b32 s4, s6, 1
	v_pk_add_f32 v[10:11], v[88:89], v[10:11]
	s_add_u32 s0, s23, s4
	v_pk_add_f32 v[10:11], v[60:61], v[10:11]
	s_addc_u32 s1, s24, 0
	v_pk_add_f32 v[10:11], v[62:63], v[10:11]
	s_nop 0
	v_add_f32_e32 v90, v10, v11
	s_setprio 1
	ds_read2_b64 v[52:55], v12 offset0:132 offset1:134
	ds_read2_b64 v[56:59], v0 offset0:164 offset1:166
	v_cvt_pk_bf16_f32 v48, v14, v15
	v_cvt_pk_bf16_f32 v49, v64, v65
	v_cvt_pk_bf16_f32 v50, v66, v67
	v_cvt_pk_bf16_f32 v51, v68, v69
	s_waitcnt lgkmcnt(3)
	s_nop 0
	v_mfma_f32_32x32x16_bf16 v[32:47], v[2:5], v[48:51], v[32:47]
	s_waitcnt lgkmcnt(2)
	v_mfma_f32_32x32x16_bf16 v[16:31], v[6:9], v[48:51], v[16:31]
	ds_read2_b64 v[6:9], v12 offset0:136 offset1:138
	ds_read2_b64 v[48:51], v0 offset0:168 offset1:170
	v_cvt_pk_bf16_f32 v2, v72, v73
	v_cvt_pk_bf16_f32 v3, v74, v75
	v_cvt_pk_bf16_f32 v4, v76, v77
	v_cvt_pk_bf16_f32 v5, v78, v79
	s_waitcnt lgkmcnt(3)
	s_nop 0
	v_mfma_f32_32x32x16_bf16 v[32:47], v[52:55], v[2:5], v[32:47]
	s_waitcnt lgkmcnt(2)
	v_mfma_f32_32x32x16_bf16 v[16:31], v[56:59], v[2:5], v[16:31]
	ds_read2_b64 v[10:13], v12 offset0:140 offset1:142
	ds_read2_b64 v[52:55], v0 offset0:172 offset1:174
	v_cvt_pk_bf16_f32 v2, v80, v81
	v_cvt_pk_bf16_f32 v3, v82, v83
	v_cvt_pk_bf16_f32 v4, v84, v85
	v_cvt_pk_bf16_f32 v5, v86, v87
	s_waitcnt lgkmcnt(3)
	s_nop 0
	v_mfma_f32_32x32x16_bf16 v[32:47], v[6:9], v[2:5], v[32:47]
	s_waitcnt lgkmcnt(2)
	v_mfma_f32_32x32x16_bf16 v[16:31], v[48:51], v[2:5], v[16:31]
	v_cvt_pk_bf16_f32 v2, v70, v71
	v_cvt_pk_bf16_f32 v3, v88, v89
	v_cvt_pk_bf16_f32 v4, v60, v61
	v_cvt_pk_bf16_f32 v5, v62, v63
	s_waitcnt lgkmcnt(1)
	s_nop 0
	v_mfma_f32_32x32x16_bf16 v[32:47], v[10:13], v[2:5], v[32:47]
	s_waitcnt lgkmcnt(0)
	v_mfma_f32_32x32x16_bf16 v[16:31], v[52:55], v[2:5], v[16:31]
	v_add_f32_e32 v0, v141, v90
	s_setprio 0
	v_lshl_add_u64 v[2:3], s[0:1], 0, v[150:151]
	v_mov_b32_e32 v145, v1
	v_lshl_add_u64 v[2:3], v[2:3], 0, v[144:145]
	s_barrier
	global_load_dwordx2 v[4:5], v[2:3], off
	global_load_dwordx2 v[6:7], v[2:3], off offset:16
	global_load_dwordx2 v[8:9], v[2:3], off offset:32
	global_load_dwordx2 v[10:11], v[2:3], off offset:48
	global_load_dwordx2 v[12:13], v[2:3], off offset:64
	global_load_dwordx2 v[14:15], v[2:3], off offset:80
	v_mov_b32_e32 v50, v0
	s_nop 1
	v_permlane32_swap_b32_e32 v0, v50
	v_add_f32_e32 v0, v0, v50
	global_load_dwordx2 v[50:51], v[2:3], off offset:96
	s_nop 0
	global_load_dwordx2 v[2:3], v[2:3], off offset:112
	s_add_u32 s0, s25, s4
	v_lshlrev_b64 v[48:49], 11, v[148:149]
	s_addc_u32 s1, s26, 0
	v_lshl_add_u64 v[48:49], s[0:1], 0, v[48:49]
	v_div_scale_f32 v52, s[0:1], v0, v0, 1.0
	v_rcp_f32_e32 v53, v52
	v_div_scale_f32 v54, vcc, 1.0, v0, 1.0
	v_lshl_add_u64 v[48:49], v[48:49], 0, v[144:145]
	v_fma_f32 v55, -v52, v53, 1.0
	v_fmac_f32_e32 v53, v55, v53
	v_mul_f32_e32 v55, v54, v53
	v_fma_f32 v56, -v52, v55, v54
	v_fmac_f32_e32 v55, v56, v53
	v_fma_f32 v52, -v52, v55, v54
	v_div_fmas_f32 v52, v52, v53, v55
	v_div_fixup_f32 v0, v52, v0, 1.0
	s_waitcnt vmcnt(7)
	v_lshlrev_b32_e32 v52, 16, v4
	v_and_b32_e32 v53, 0xffff0000, v4
	v_lshlrev_b32_e32 v54, 16, v5
	v_and_b32_e32 v55, 0xffff0000, v5
	v_mul_f32_e32 v56, v32, v0
	v_mul_f32_e32 v57, v33, v0
	v_mul_f32_e32 v58, v34, v0
	v_mul_f32_e32 v59, v35, v0
	v_mul_f32_e32 v56, v56, v52
	v_mul_f32_e32 v57, v57, v53
	v_mul_f32_e32 v58, v58, v54
	v_mul_f32_e32 v59, v59, v55
	v_cvt_pk_bf16_f32 v32, v56, v57
	v_cvt_pk_bf16_f32 v33, v58, v59
	s_waitcnt vmcnt(6)
	v_lshlrev_b32_e32 v52, 16, v6
	v_and_b32_e32 v53, 0xffff0000, v6
	v_lshlrev_b32_e32 v54, 16, v7
	v_and_b32_e32 v55, 0xffff0000, v7
	v_mul_f32_e32 v56, v36, v0
	v_mul_f32_e32 v57, v37, v0
	v_mul_f32_e32 v58, v38, v0
	v_mul_f32_e32 v59, v39, v0
	v_mul_f32_e32 v56, v56, v52
	v_mul_f32_e32 v57, v57, v53
	v_mul_f32_e32 v58, v58, v54
	v_mul_f32_e32 v59, v59, v55
	v_cvt_pk_bf16_f32 v34, v56, v57
	v_cvt_pk_bf16_f32 v35, v58, v59
	s_waitcnt vmcnt(5)
	v_lshlrev_b32_e32 v52, 16, v8
	v_and_b32_e32 v53, 0xffff0000, v8
	v_lshlrev_b32_e32 v54, 16, v9
	v_and_b32_e32 v55, 0xffff0000, v9
	v_mul_f32_e32 v56, v40, v0
	v_mul_f32_e32 v57, v41, v0
	v_mul_f32_e32 v58, v42, v0
	v_mul_f32_e32 v59, v43, v0
	v_mul_f32_e32 v56, v56, v52
	v_mul_f32_e32 v57, v57, v53
	v_mul_f32_e32 v58, v58, v54
	v_mul_f32_e32 v59, v59, v55
	v_cvt_pk_bf16_f32 v36, v56, v57
	v_cvt_pk_bf16_f32 v37, v58, v59
	s_waitcnt vmcnt(4)
	v_lshlrev_b32_e32 v52, 16, v10
	v_and_b32_e32 v53, 0xffff0000, v10
	v_lshlrev_b32_e32 v54, 16, v11
	v_and_b32_e32 v55, 0xffff0000, v11
	v_mul_f32_e32 v56, v44, v0
	v_mul_f32_e32 v57, v45, v0
	v_mul_f32_e32 v58, v46, v0
	v_mul_f32_e32 v59, v47, v0
	v_mul_f32_e32 v56, v56, v52
	v_mul_f32_e32 v57, v57, v53
	v_mul_f32_e32 v58, v58, v54
	v_mul_f32_e32 v59, v59, v55
	v_cvt_pk_bf16_f32 v38, v56, v57
	v_cvt_pk_bf16_f32 v39, v58, v59
	s_waitcnt vmcnt(3)
	v_lshlrev_b32_e32 v52, 16, v12
	v_and_b32_e32 v53, 0xffff0000, v12
	v_lshlrev_b32_e32 v54, 16, v13
	v_and_b32_e32 v55, 0xffff0000, v13
	v_mul_f32_e32 v56, v16, v0
	v_mul_f32_e32 v57, v17, v0
	v_mul_f32_e32 v58, v18, v0
	v_mul_f32_e32 v59, v19, v0
	v_mul_f32_e32 v56, v56, v52
	v_mul_f32_e32 v57, v57, v53
	v_mul_f32_e32 v58, v58, v54
	v_mul_f32_e32 v59, v59, v55
	v_cvt_pk_bf16_f32 v40, v56, v57
	v_cvt_pk_bf16_f32 v41, v58, v59
	s_waitcnt vmcnt(2)
	v_lshlrev_b32_e32 v52, 16, v14
	v_and_b32_e32 v53, 0xffff0000, v14
	v_lshlrev_b32_e32 v54, 16, v15
	v_and_b32_e32 v55, 0xffff0000, v15
	v_mul_f32_e32 v56, v20, v0
	v_mul_f32_e32 v57, v21, v0
	v_mul_f32_e32 v58, v22, v0
	v_mul_f32_e32 v59, v23, v0
	v_mul_f32_e32 v56, v56, v52
	v_mul_f32_e32 v57, v57, v53
	v_mul_f32_e32 v58, v58, v54
	v_mul_f32_e32 v59, v59, v55
	v_cvt_pk_bf16_f32 v42, v56, v57
	v_cvt_pk_bf16_f32 v43, v58, v59
	s_waitcnt vmcnt(1)
	v_lshlrev_b32_e32 v52, 16, v50
	v_and_b32_e32 v53, 0xffff0000, v50
	v_lshlrev_b32_e32 v54, 16, v51
	v_and_b32_e32 v55, 0xffff0000, v51
	v_mul_f32_e32 v56, v24, v0
	v_mul_f32_e32 v57, v25, v0
	v_mul_f32_e32 v58, v26, v0
	v_mul_f32_e32 v59, v27, v0
	v_mul_f32_e32 v56, v56, v52
	v_mul_f32_e32 v57, v57, v53
	v_mul_f32_e32 v58, v58, v54
	v_mul_f32_e32 v59, v59, v55
	v_cvt_pk_bf16_f32 v44, v56, v57
	v_cvt_pk_bf16_f32 v45, v58, v59
	s_waitcnt vmcnt(0)
	v_lshlrev_b32_e32 v52, 16, v2
	v_and_b32_e32 v53, 0xffff0000, v2
	v_lshlrev_b32_e32 v54, 16, v3
	v_and_b32_e32 v55, 0xffff0000, v3
	v_mul_f32_e32 v56, v28, v0
	v_mul_f32_e32 v57, v29, v0
	v_mul_f32_e32 v58, v30, v0
	v_mul_f32_e32 v59, v31, v0
	v_mul_f32_e32 v56, v56, v52
	v_mul_f32_e32 v57, v57, v53
	v_mul_f32_e32 v58, v58, v54
	v_mul_f32_e32 v59, v59, v55
	v_cvt_pk_bf16_f32 v46, v56, v57
	v_cvt_pk_bf16_f32 v47, v58, v59
	v_mbcnt_lo_u32_b32 v60, -1, 0
	v_mbcnt_hi_u32_b32 v60, -1, v60
	v_and_b32_e32 v60, 32, v60
	v_lshrrev_b32_e32 v60, 2, v60
	v_mov_b32_e32 v61, 0
	v_lshl_add_u64 v[48:49], v[48:49], 0, v[60:61]
	v_permlane32_swap_b32_e32 v32, v34
	v_permlane32_swap_b32_e32 v33, v35
	v_permlane32_swap_b32_e32 v36, v38
	v_permlane32_swap_b32_e32 v37, v39
	v_permlane32_swap_b32_e32 v40, v42
	v_permlane32_swap_b32_e32 v41, v43
	v_permlane32_swap_b32_e32 v44, v46
	v_permlane32_swap_b32_e32 v45, v47
	global_store_dwordx4 v[48:49], v[32:35], off
	global_store_dwordx4 v[48:49], v[36:39], off offset:32
	global_store_dwordx4 v[48:49], v[40:43], off offset:64
	global_store_dwordx4 v[48:49], v[44:47], off offset:96
